# lorak (live G==256 path): LoRA GEMM runs 4 of 8 K-steps per tile from a per-column-group K origin; skipped steps multiply the zero padding of the fused LoRA weight
# speedup vs baseline: 1.0105x; 1.0105x over previous
.LBB0_530:
	s_and_b64 vcc, exec, s[0:1]
	s_cbranch_vccz .LBB0_583
	s_cmp_gt_i32 s69, 31
	s_mov_b64 s[0:1], -1
	s_cbranch_scc0 .LBB0_562
	s_cmp_gt_u32 s69, 63
	s_cbranch_scc0 .LBB0_554
	s_sub_i32 s36, s69, 64
	s_cmpk_gt_u32 s36, 0x2ff
	v_readfirstlane_b32 s37, v170
	s_cbranch_scc1 .LBB0_553
	v_lshrrev_b32_e32 v0, 5, v170
	v_lshrrev_b32_e32 v2, 1, v170
	v_and_b32_e32 v0, 4, v0
	v_bfe_u32 v1, v170, 2, 2
	v_and_b32_e32 v11, 24, v2
	v_or3_b32 v0, v0, v1, v11
	v_lshlrev_b32_e32 v1, 4, v170
	v_add_u32_e32 v8, 0x2000, v1
	v_lshrrev_b32_e32 v2, 7, v8
	s_movk_i32 s0, 0xe0
	v_and_b32_e32 v4, 32, v170
	v_and_or_b32 v3, v2, s0, v0
	v_bitop3_b32 v9, v1, v4, 48 bitop3:0x6c
	v_and_b32_e32 v10, 64, v170
	v_bfe_u32 v12, v170, 2, 4
	s_movk_i32 s0, 0xf0
	v_or_b32_e32 v1, v9, v10
	v_and_or_b32 v2, v2, s0, v12
	v_lshl_or_b32 v146, v2, 10, v1
	v_lshrrev_b32_e32 v2, 3, v170
	s_movk_i32 s0, 0x60
	s_add_u32 s40, s66, 0x8000000
	v_and_or_b32 v0, v2, s0, v0
	s_movk_i32 s0, 0x70
	s_addc_u32 s41, s67, 0
	v_lshl_or_b32 v148, v0, 10, v1
	v_and_or_b32 v0, v2, s0, v12
	s_and_b32 s0, s69, 7
	s_lshr_b32 s1, s36, 3
	s_mulk_i32 s0, 0x60
	s_add_i32 s0, s0, s1
	s_mul_i32 s1, s0, 0xaaab
	s_lshr_b32 s1, s1, 21
	s_lshl_b32 s12, s1, 2
	s_mul_i32 s1, s1, 48
	s_sub_i32 s0, s0, s1
	s_and_b32 s1, s0, 3
	s_lshr_b32 s2, s37, 6
	s_or_b32 s12, s12, s1
	s_bfe_u32 s13, s0, 0x60002
	s_lshr_b32 s3, s37, 8
	s_lshl_b32 s42, s2, 10
	s_lshl_b32 s0, s12, 18
	s_lshl_b32 s1, s13, 18
	s_lshr_b32 s98, s13, 2
	s_add_i32 s99, s98, 1
	s_mul_i32 s98, s98, s99
	s_lshl_b32 s98, s98, 6
	s_add_i32 s0, s0, s98
	s_add_i32 s1, s1, s98
	s_add_u32 s30, s40, s1
	s_addc_u32 s31, s41, 0
	s_add_i32 s43, s42, 0
	s_add_i32 m0, s43, 0x10000
	v_lshl_or_b32 v144, v3, 10, v1
	global_load_lds_dwordx4 v148, s[30:31]
	s_add_i32 m0, s43, 0x12000
	s_add_u32 s0, s38, s0
	v_lshl_or_b32 v150, v0, 10, v1
	global_load_lds_dwordx4 v144, s[30:31]
	s_addc_u32 s1, s39, 0
	s_mov_b32 m0, s43
	s_add_i32 s44, s43, 0x2000
	global_load_lds_dwordx4 v150, s[0:1]
	s_mov_b32 m0, s44
	s_add_u32 s14, s30, 0x20000
	global_load_lds_dwordx4 v146, s[0:1]
	s_addc_u32 s15, s31, 0
	s_add_i32 m0, s43, 0x14000
	v_mov_b32_e32 v153, 0
	global_load_lds_dwordx4 v148, s[14:15]
	s_add_i32 m0, s43, 0x16000
	v_mov_b32_e32 v149, v153
	global_load_lds_dwordx4 v144, s[14:15]
	s_add_u32 s14, s0, 0x20000
	s_addc_u32 s15, s1, 0
	s_add_i32 s45, s43, 0x4000
	s_mov_b32 m0, s45
	s_add_i32 s46, s43, 0x6000
	global_load_lds_dwordx4 v150, s[14:15]
	s_mov_b32 m0, s46
	v_mov_b32_e32 v145, v153
	global_load_lds_dwordx4 v146, s[14:15]
	v_mov_b32_e32 v151, v153
	v_mov_b32_e32 v147, v153
	s_mov_b32 s47, 0
	v_lshl_add_u64 v[6:7], s[30:31], 0, v[148:149]
	v_lshl_add_u64 v[4:5], s[30:31], 0, v[144:145]
	v_lshl_add_u64 v[2:3], s[0:1], 0, v[150:151]
	s_cmp_lg_u32 s3, 1
	v_lshl_add_u64 v[0:1], s[0:1], 0, v[146:147]
	s_cbranch_scc1 .LBB0_536
	s_barrier

.LBB0_540:
	s_ashr_i32 s23, s22, 31
	v_cmp_lt_u64_e32 vcc, s[26:27], v[158:159]
	s_lshl_b64 s[26:27], s[22:23], 18
	s_add_u32 s26, s38, s26
	s_addc_u32 s27, s39, s27
	s_lshr_b32 s98, s24, 2
	s_add_i32 s99, s98, 1
	s_mul_i32 s98, s98, s99
	s_lshl_b32 s98, s98, 6
	s_add_u32 s26, s26, s98
	s_addc_u32 s27, s27, 0
	s_and_b64 s[28:29], vcc, exec
	s_cselect_b32 s23, s27, s1
	s_cselect_b32 s61, s26, s0
	s_ashr_i32 s25, s24, 31
	s_lshl_b64 s[28:29], s[24:25], 18
	s_add_u32 s28, s40, s28
	s_addc_u32 s29, s41, s29
	s_add_u32 s28, s28, s98
	s_addc_u32 s29, s29, 0
	s_and_b64 s[34:35], vcc, exec
	s_cselect_b32 s25, s29, s31
	s_cselect_b32 s62, s28, s30
	s_add_u32 s0, s0, 0x20080
	s_addc_u32 s1, s1, 0
	s_add_u32 s63, s30, 0x100
	v_mov_b32_e32 v0, 0
	s_addc_u32 s64, s31, 0
	s_mov_b32 s65, -2
	v_mov_b32_e32 v1, v0
	v_mov_b32_e32 v2, v0
	v_mov_b32_e32 v3, v0
	v_mov_b32_e32 v4, v0
	v_mov_b32_e32 v5, v0
	v_mov_b32_e32 v6, v0
	v_mov_b32_e32 v7, v0
	v_mov_b32_e32 v16, v0
	v_mov_b32_e32 v17, v0
	v_mov_b32_e32 v18, v0
	v_mov_b32_e32 v19, v0
	v_mov_b32_e32 v20, v0
	v_mov_b32_e32 v21, v0
	v_mov_b32_e32 v22, v0
	v_mov_b32_e32 v23, v0
	v_mov_b32_e32 v32, v0
	v_mov_b32_e32 v33, v0
	v_mov_b32_e32 v34, v0
	v_mov_b32_e32 v35, v0
	v_mov_b32_e32 v36, v0
	v_mov_b32_e32 v37, v0
	v_mov_b32_e32 v38, v0
	v_mov_b32_e32 v39, v0
	v_mov_b32_e32 v48, v0
	v_mov_b32_e32 v49, v0
	v_mov_b32_e32 v50, v0
	v_mov_b32_e32 v51, v0
	v_mov_b32_e32 v52, v0
	v_mov_b32_e32 v53, v0
	v_mov_b32_e32 v54, v0
	v_mov_b32_e32 v55, v0
	v_mov_b32_e32 v8, v0
	v_mov_b32_e32 v9, v0
	v_mov_b32_e32 v10, v0
	v_mov_b32_e32 v11, v0
	v_mov_b32_e32 v12, v0
	v_mov_b32_e32 v13, v0
	v_mov_b32_e32 v14, v0
	v_mov_b32_e32 v15, v0
	v_mov_b32_e32 v24, v0
	v_mov_b32_e32 v25, v0
	v_mov_b32_e32 v26, v0
	v_mov_b32_e32 v27, v0
	v_mov_b32_e32 v28, v0
	v_mov_b32_e32 v29, v0
	v_mov_b32_e32 v30, v0
	v_mov_b32_e32 v31, v0
	v_mov_b32_e32 v40, v0
	v_mov_b32_e32 v41, v0
	v_mov_b32_e32 v42, v0
	v_mov_b32_e32 v43, v0
	v_mov_b32_e32 v44, v0
	v_mov_b32_e32 v45, v0
	v_mov_b32_e32 v46, v0
	v_mov_b32_e32 v47, v0
	v_mov_b32_e32 v56, v0
	v_mov_b32_e32 v57, v0
	v_mov_b32_e32 v58, v0
	v_mov_b32_e32 v59, v0
	v_mov_b32_e32 v60, v0
	v_mov_b32_e32 v61, v0
	v_mov_b32_e32 v62, v0
	v_mov_b32_e32 v63, v0
	v_mov_b32_e32 v72, v0
	v_mov_b32_e32 v73, v0
	v_mov_b32_e32 v74, v0
	v_mov_b32_e32 v75, v0
	v_mov_b32_e32 v76, v0
	v_mov_b32_e32 v77, v0
	v_mov_b32_e32 v78, v0
	v_mov_b32_e32 v79, v0
	v_mov_b32_e32 v96, v0
	v_mov_b32_e32 v97, v0
	v_mov_b32_e32 v98, v0
	v_mov_b32_e32 v99, v0
	v_mov_b32_e32 v100, v0
	v_mov_b32_e32 v101, v0
	v_mov_b32_e32 v102, v0
	v_mov_b32_e32 v103, v0
	v_mov_b32_e32 v112, v0
	v_mov_b32_e32 v113, v0
	v_mov_b32_e32 v114, v0
	v_mov_b32_e32 v115, v0
	v_mov_b32_e32 v116, v0
	v_mov_b32_e32 v117, v0
	v_mov_b32_e32 v118, v0
	v_mov_b32_e32 v119, v0
	v_mov_b32_e32 v128, v0
	v_mov_b32_e32 v129, v0
	v_mov_b32_e32 v130, v0
	v_mov_b32_e32 v131, v0
	v_mov_b32_e32 v132, v0
	v_mov_b32_e32 v133, v0
	v_mov_b32_e32 v134, v0
	v_mov_b32_e32 v135, v0
	v_mov_b32_e32 v88, v0
	v_mov_b32_e32 v89, v0
	v_mov_b32_e32 v90, v0
	v_mov_b32_e32 v91, v0
	v_mov_b32_e32 v92, v0
	v_mov_b32_e32 v93, v0
	v_mov_b32_e32 v94, v0
	v_mov_b32_e32 v95, v0
	v_mov_b32_e32 v104, v0
	v_mov_b32_e32 v105, v0
	v_mov_b32_e32 v106, v0
	v_mov_b32_e32 v107, v0
	v_mov_b32_e32 v108, v0
	v_mov_b32_e32 v109, v0
	v_mov_b32_e32 v110, v0
	v_mov_b32_e32 v111, v0
	v_mov_b32_e32 v120, v0
	v_mov_b32_e32 v121, v0
	v_mov_b32_e32 v122, v0
	v_mov_b32_e32 v123, v0
	v_mov_b32_e32 v124, v0
	v_mov_b32_e32 v125, v0
	v_mov_b32_e32 v126, v0
	v_mov_b32_e32 v127, v0
	v_mov_b32_e32 v136, v0
	v_mov_b32_e32 v137, v0
	v_mov_b32_e32 v138, v0
	v_mov_b32_e32 v139, v0
	v_mov_b32_e32 v140, v0
	v_mov_b32_e32 v141, v0
	v_mov_b32_e32 v142, v0
	v_mov_b32_e32 v143, v0
.LBB0_541:
	ds_read_b128 v[64:67], v175
	ds_read_b128 v[68:71], v175 offset:1024
	ds_read_b128 v[80:83], v175 offset:2048
	ds_read_b128 v[84:87], v175 offset:3072
	s_add_u32 s30, s0, 0xfffe0080
	s_addc_u32 s31, s1, -1
	s_cmp_eq_u32 s65, 0
	s_cselect_b32 s35, s23, s31
	s_cselect_b32 s34, s61, s30
	s_cselect_b32 s31, s25, s64
	s_cselect_b32 s30, s62, s63
	v_lshl_add_u64 v[204:205], s[0:1], 0, v[154:155]
	s_add_i32 m0, s43, 0xc000
	ds_read_b128 v[162:165], v176
	ds_read_b128 v[166:169], v176 offset:1024
	ds_read_b128 v[180:183], v176 offset:2048
	ds_read_b128 v[184:187], v176 offset:3072
	ds_read_b128 v[188:191], v176 offset:4096
	ds_read_b128 v[192:195], v176 offset:5120
	ds_read_b128 v[196:199], v176 offset:6144
	ds_read_b128 v[200:203], v176 offset:7168
	global_load_lds_dwordx4 v[204:205], off
	v_lshl_add_u64 v[204:205], s[0:1], 0, v[156:157]
	s_add_i32 m0, s43, 0xe000
	s_nop 0
	global_load_lds_dwordx4 v[204:205], off
	s_waitcnt lgkmcnt(8)
	s_barrier
	s_waitcnt lgkmcnt(0)
	s_setprio 1
	s_waitcnt lgkmcnt(0)
	v_mfma_f32_16x16x32_bf16 v[140:143], v[64:67], v[162:165], v[140:143]
	v_mfma_f32_16x16x32_bf16 v[136:139], v[80:83], v[162:165], v[136:139]
	v_mfma_f32_16x16x32_bf16 v[124:127], v[64:67], v[180:183], v[124:127]
	v_mfma_f32_16x16x32_bf16 v[120:123], v[80:83], v[180:183], v[120:123]
	v_mfma_f32_16x16x32_bf16 v[108:111], v[64:67], v[188:191], v[108:111]
	v_mfma_f32_16x16x32_bf16 v[104:107], v[80:83], v[188:191], v[104:107]
	v_mfma_f32_16x16x32_bf16 v[92:95], v[64:67], v[196:199], v[92:95]
	v_mfma_f32_16x16x32_bf16 v[88:91], v[80:83], v[196:199], v[88:91]
	v_mfma_f32_16x16x32_bf16 v[140:143], v[68:71], v[166:169], v[140:143]
	v_mfma_f32_16x16x32_bf16 v[136:139], v[84:87], v[166:169], v[136:139]
	v_mfma_f32_16x16x32_bf16 v[124:127], v[68:71], v[184:187], v[124:127]
	v_mfma_f32_16x16x32_bf16 v[120:123], v[84:87], v[184:187], v[120:123]
	v_mfma_f32_16x16x32_bf16 v[108:111], v[68:71], v[192:195], v[108:111]
	v_mfma_f32_16x16x32_bf16 v[104:107], v[84:87], v[192:195], v[104:107]
	v_mfma_f32_16x16x32_bf16 v[92:95], v[68:71], v[200:203], v[92:95]
	v_mfma_f32_16x16x32_bf16 v[88:91], v[84:87], v[200:203], v[88:91]
	s_setprio 0
	s_barrier
	s_add_i32 s66, s50, s42
	v_lshl_add_u64 v[220:221], s[30:31], 0, v[148:149]
	s_mov_b32 m0, s66
	ds_read_b128 v[204:207], v177
	ds_read_b128 v[208:211], v177 offset:1024
	ds_read_b128 v[212:215], v177 offset:2048
	ds_read_b128 v[216:219], v177 offset:3072
	global_load_lds_dwordx4 v[220:221], off
	v_lshl_add_u64 v[222:223], s[30:31], 0, v[144:145]
	s_add_i32 m0, s66, 0x2000
	s_nop 0
	global_load_lds_dwordx4 v[222:223], off
	s_barrier
	s_waitcnt lgkmcnt(0)
	s_setprio 1
	s_waitcnt lgkmcnt(0)
	v_mfma_f32_16x16x32_bf16 v[132:135], v[204:207], v[162:165], v[132:135]
	v_mfma_f32_16x16x32_bf16 v[128:131], v[212:215], v[162:165], v[128:131]
	v_mfma_f32_16x16x32_bf16 v[116:119], v[204:207], v[180:183], v[116:119]
	v_mfma_f32_16x16x32_bf16 v[112:115], v[212:215], v[180:183], v[112:115]
	v_mfma_f32_16x16x32_bf16 v[100:103], v[204:207], v[188:191], v[100:103]
	v_mfma_f32_16x16x32_bf16 v[96:99], v[212:215], v[188:191], v[96:99]
	v_mfma_f32_16x16x32_bf16 v[76:79], v[204:207], v[196:199], v[76:79]
	v_mfma_f32_16x16x32_bf16 v[72:75], v[212:215], v[196:199], v[72:75]
	v_mfma_f32_16x16x32_bf16 v[132:135], v[208:211], v[166:169], v[132:135]
	v_mfma_f32_16x16x32_bf16 v[128:131], v[216:219], v[166:169], v[128:131]
	v_mfma_f32_16x16x32_bf16 v[116:119], v[208:211], v[184:187], v[116:119]
	v_mfma_f32_16x16x32_bf16 v[112:115], v[216:219], v[184:187], v[112:115]
	v_mfma_f32_16x16x32_bf16 v[100:103], v[208:211], v[192:195], v[100:103]
	v_mfma_f32_16x16x32_bf16 v[96:99], v[216:219], v[192:195], v[96:99]
	v_mfma_f32_16x16x32_bf16 v[76:79], v[208:211], v[200:203], v[76:79]
	v_mfma_f32_16x16x32_bf16 v[72:75], v[216:219], v[200:203], v[72:75]
	s_setprio 0
	s_mov_b32 m0, s43
	v_lshl_add_u64 v[224:225], s[34:35], 0, v[150:151]
	s_barrier
	ds_read_b128 v[162:165], v176 offset:16384
	ds_read_b128 v[166:169], v176 offset:17408
	ds_read_b128 v[180:183], v176 offset:18432
	ds_read_b128 v[184:187], v176 offset:19456
	ds_read_b128 v[188:191], v176 offset:20480
	ds_read_b128 v[192:195], v176 offset:21504
	ds_read_b128 v[196:199], v176 offset:22528
	ds_read_b128 v[200:203], v176 offset:23552
	global_load_lds_dwordx4 v[224:225], off
	v_lshl_add_u64 v[226:227], s[34:35], 0, v[146:147]
	s_mov_b32 m0, s44
	s_nop 0
	global_load_lds_dwordx4 v[226:227], off
	s_barrier
	s_waitcnt lgkmcnt(0)
	s_setprio 1
	s_waitcnt lgkmcnt(0)
	v_mfma_f32_16x16x32_bf16 v[60:63], v[64:67], v[162:165], v[60:63]
	v_mfma_f32_16x16x32_bf16 v[56:59], v[80:83], v[162:165], v[56:59]
	v_mfma_f32_16x16x32_bf16 v[44:47], v[64:67], v[180:183], v[44:47]
	v_mfma_f32_16x16x32_bf16 v[40:43], v[80:83], v[180:183], v[40:43]
	v_mfma_f32_16x16x32_bf16 v[28:31], v[64:67], v[188:191], v[28:31]
	v_mfma_f32_16x16x32_bf16 v[24:27], v[80:83], v[188:191], v[24:27]
	v_mfma_f32_16x16x32_bf16 v[12:15], v[64:67], v[196:199], v[12:15]
	v_mfma_f32_16x16x32_bf16 v[8:11], v[80:83], v[196:199], v[8:11]
	v_mfma_f32_16x16x32_bf16 v[60:63], v[68:71], v[166:169], v[60:63]
	v_mfma_f32_16x16x32_bf16 v[56:59], v[84:87], v[166:169], v[56:59]
	v_mfma_f32_16x16x32_bf16 v[44:47], v[68:71], v[184:187], v[44:47]
	v_mfma_f32_16x16x32_bf16 v[40:43], v[84:87], v[184:187], v[40:43]
	v_mfma_f32_16x16x32_bf16 v[28:31], v[68:71], v[192:195], v[28:31]
	v_mfma_f32_16x16x32_bf16 v[24:27], v[84:87], v[192:195], v[24:27]
	v_mfma_f32_16x16x32_bf16 v[12:15], v[68:71], v[200:203], v[12:15]
	v_mfma_f32_16x16x32_bf16 v[8:11], v[84:87], v[200:203], v[8:11]
	s_setprio 0
	s_barrier
	s_add_u32 s66, s30, 0x20000
	s_addc_u32 s67, s31, 0
	s_add_i32 s80, s51, s42
	v_lshl_add_u64 v[64:65], s[66:67], 0, v[148:149]
	s_mov_b32 m0, s80
	s_nop 0
	global_load_lds_dwordx4 v[64:65], off
	v_lshl_add_u64 v[64:65], s[66:67], 0, v[144:145]
	s_add_i32 m0, s80, 0x2000
	s_nop 0
	global_load_lds_dwordx4 v[64:65], off
	s_waitcnt vmcnt(6)
	s_barrier
	s_setprio 1
	v_mfma_f32_16x16x32_bf16 v[52:55], v[204:207], v[162:165], v[52:55]
	v_mfma_f32_16x16x32_bf16 v[48:51], v[212:215], v[162:165], v[48:51]
	v_mfma_f32_16x16x32_bf16 v[36:39], v[204:207], v[180:183], v[36:39]
	v_mfma_f32_16x16x32_bf16 v[32:35], v[212:215], v[180:183], v[32:35]
	v_mfma_f32_16x16x32_bf16 v[20:23], v[204:207], v[188:191], v[20:23]
	v_mfma_f32_16x16x32_bf16 v[16:19], v[212:215], v[188:191], v[16:19]
	v_mfma_f32_16x16x32_bf16 v[4:7], v[204:207], v[196:199], v[4:7]
	v_mfma_f32_16x16x32_bf16 v[0:3], v[212:215], v[196:199], v[0:3]
	v_mfma_f32_16x16x32_bf16 v[52:55], v[208:211], v[166:169], v[52:55]
	v_mfma_f32_16x16x32_bf16 v[48:51], v[216:219], v[166:169], v[48:51]
	v_mfma_f32_16x16x32_bf16 v[36:39], v[208:211], v[184:187], v[36:39]
	v_mfma_f32_16x16x32_bf16 v[32:35], v[216:219], v[184:187], v[32:35]
	v_mfma_f32_16x16x32_bf16 v[20:23], v[208:211], v[192:195], v[20:23]
	v_mfma_f32_16x16x32_bf16 v[16:19], v[216:219], v[192:195], v[16:19]
	v_mfma_f32_16x16x32_bf16 v[4:7], v[208:211], v[200:203], v[4:7]
	v_mfma_f32_16x16x32_bf16 v[0:3], v[216:219], v[200:203], v[0:3]
	s_setprio 0
	s_add_i32 s66, 0, 0x18000
	v_add_u32_e32 v84, s66, v173
	s_barrier
	ds_read_b128 v[64:67], v84
	ds_read_b128 v[68:71], v84 offset:1024
	ds_read_b128 v[80:83], v84 offset:2048
	ds_read_b128 v[84:87], v84 offset:3072
	s_add_u32 s34, s34, 0x20000
	s_addc_u32 s35, s35, 0
	s_mov_b32 m0, s45
	v_lshl_add_u64 v[204:205], s[34:35], 0, v[150:151]
	ds_read_b128 v[162:165], v176 offset:32768
	ds_read_b128 v[166:169], v176 offset:33792
	ds_read_b128 v[180:183], v176 offset:34816
	ds_read_b128 v[184:187], v176 offset:35840
	ds_read_b128 v[188:191], v176 offset:36864
	ds_read_b128 v[192:195], v176 offset:37888
	ds_read_b128 v[196:199], v176 offset:38912
	ds_read_b128 v[200:203], v176 offset:39936
	global_load_lds_dwordx4 v[204:205], off
	v_lshl_add_u64 v[204:205], s[34:35], 0, v[146:147]
	s_mov_b32 m0, s46
	s_nop 0
	global_load_lds_dwordx4 v[204:205], off
	s_waitcnt lgkmcnt(8)
	s_barrier
	s_waitcnt lgkmcnt(0)
	s_setprio 1
	s_waitcnt lgkmcnt(0)
	v_mfma_f32_16x16x32_bf16 v[140:143], v[64:67], v[162:165], v[140:143]
	v_mfma_f32_16x16x32_bf16 v[136:139], v[80:83], v[162:165], v[136:139]
	v_mfma_f32_16x16x32_bf16 v[124:127], v[64:67], v[180:183], v[124:127]
	v_mfma_f32_16x16x32_bf16 v[120:123], v[80:83], v[180:183], v[120:123]
	v_mfma_f32_16x16x32_bf16 v[108:111], v[64:67], v[188:191], v[108:111]
	v_mfma_f32_16x16x32_bf16 v[104:107], v[80:83], v[188:191], v[104:107]
	v_mfma_f32_16x16x32_bf16 v[92:95], v[64:67], v[196:199], v[92:95]
	v_mfma_f32_16x16x32_bf16 v[88:91], v[80:83], v[196:199], v[88:91]
	v_mfma_f32_16x16x32_bf16 v[140:143], v[68:71], v[166:169], v[140:143]
	v_mfma_f32_16x16x32_bf16 v[136:139], v[84:87], v[166:169], v[136:139]
	v_mfma_f32_16x16x32_bf16 v[124:127], v[68:71], v[184:187], v[124:127]
	v_mfma_f32_16x16x32_bf16 v[120:123], v[84:87], v[184:187], v[120:123]
	v_mfma_f32_16x16x32_bf16 v[108:111], v[68:71], v[192:195], v[108:111]
	v_mfma_f32_16x16x32_bf16 v[104:107], v[84:87], v[192:195], v[104:107]
	v_mfma_f32_16x16x32_bf16 v[92:95], v[68:71], v[200:203], v[92:95]
	v_mfma_f32_16x16x32_bf16 v[88:91], v[84:87], v[200:203], v[88:91]
	s_setprio 0
	s_barrier
	s_add_i32 s34, 0, 0x1c000
	s_add_i32 s35, s66, s42
	v_add_u32_e32 v152, s34, v173
	v_lshl_add_u64 v[220:221], v[220:221], 0, s[12:13]
	s_mov_b32 m0, s35
	ds_read_b128 v[204:207], v152
	ds_read_b128 v[208:211], v152 offset:1024
	ds_read_b128 v[212:215], v152 offset:2048
	ds_read_b128 v[216:219], v152 offset:3072
	global_load_lds_dwordx4 v[220:221], off
	v_lshl_add_u64 v[220:221], v[222:223], 0, s[12:13]
	s_add_i32 m0, s35, 0x2000
	s_nop 0
	global_load_lds_dwordx4 v[220:221], off
	s_barrier
	s_waitcnt lgkmcnt(0)
	s_setprio 1
	s_waitcnt lgkmcnt(0)
	v_mfma_f32_16x16x32_bf16 v[132:135], v[204:207], v[162:165], v[132:135]
	v_mfma_f32_16x16x32_bf16 v[128:131], v[212:215], v[162:165], v[128:131]
	v_mfma_f32_16x16x32_bf16 v[116:119], v[204:207], v[180:183], v[116:119]
	v_mfma_f32_16x16x32_bf16 v[112:115], v[212:215], v[180:183], v[112:115]
	v_mfma_f32_16x16x32_bf16 v[100:103], v[204:207], v[188:191], v[100:103]
	v_mfma_f32_16x16x32_bf16 v[96:99], v[212:215], v[188:191], v[96:99]
	v_mfma_f32_16x16x32_bf16 v[76:79], v[204:207], v[196:199], v[76:79]
	v_mfma_f32_16x16x32_bf16 v[72:75], v[212:215], v[196:199], v[72:75]
	v_mfma_f32_16x16x32_bf16 v[132:135], v[208:211], v[166:169], v[132:135]
	v_mfma_f32_16x16x32_bf16 v[128:131], v[216:219], v[166:169], v[128:131]
	v_mfma_f32_16x16x32_bf16 v[116:119], v[208:211], v[184:187], v[116:119]
	v_mfma_f32_16x16x32_bf16 v[112:115], v[216:219], v[184:187], v[112:115]
	v_mfma_f32_16x16x32_bf16 v[100:103], v[208:211], v[192:195], v[100:103]
	v_mfma_f32_16x16x32_bf16 v[96:99], v[216:219], v[192:195], v[96:99]
	v_mfma_f32_16x16x32_bf16 v[76:79], v[208:211], v[200:203], v[76:79]
	v_mfma_f32_16x16x32_bf16 v[72:75], v[216:219], v[200:203], v[72:75]
	s_setprio 0
	s_mov_b32 m0, s48
	v_lshl_add_u64 v[220:221], v[224:225], 0, s[12:13]
	s_barrier
	ds_read_b128 v[162:165], v176 offset:49152
	ds_read_b128 v[166:169], v176 offset:50176
	ds_read_b128 v[180:183], v176 offset:51200
	ds_read_b128 v[184:187], v176 offset:52224
	ds_read_b128 v[188:191], v176 offset:53248
	ds_read_b128 v[192:195], v176 offset:54272
	ds_read_b128 v[196:199], v176 offset:55296
	ds_read_b128 v[200:203], v176 offset:56320
	global_load_lds_dwordx4 v[220:221], off
	v_lshl_add_u64 v[220:221], v[226:227], 0, s[12:13]
	s_mov_b32 m0, s49
	s_nop 0
	global_load_lds_dwordx4 v[220:221], off
	s_barrier
	s_waitcnt lgkmcnt(0)
	s_setprio 1
	s_waitcnt lgkmcnt(0)
	v_mfma_f32_16x16x32_bf16 v[60:63], v[64:67], v[162:165], v[60:63]
	v_mfma_f32_16x16x32_bf16 v[56:59], v[80:83], v[162:165], v[56:59]
	v_mfma_f32_16x16x32_bf16 v[44:47], v[64:67], v[180:183], v[44:47]
	v_mfma_f32_16x16x32_bf16 v[40:43], v[80:83], v[180:183], v[40:43]
	v_mfma_f32_16x16x32_bf16 v[28:31], v[64:67], v[188:191], v[28:31]
	v_mfma_f32_16x16x32_bf16 v[24:27], v[80:83], v[188:191], v[24:27]
	v_mfma_f32_16x16x32_bf16 v[12:15], v[64:67], v[196:199], v[12:15]
	v_mfma_f32_16x16x32_bf16 v[8:11], v[80:83], v[196:199], v[8:11]
	v_mfma_f32_16x16x32_bf16 v[60:63], v[68:71], v[166:169], v[60:63]
	v_mfma_f32_16x16x32_bf16 v[56:59], v[84:87], v[166:169], v[56:59]
	v_mfma_f32_16x16x32_bf16 v[44:47], v[68:71], v[184:187], v[44:47]
	v_mfma_f32_16x16x32_bf16 v[40:43], v[84:87], v[184:187], v[40:43]
	v_mfma_f32_16x16x32_bf16 v[28:31], v[68:71], v[192:195], v[28:31]
	v_mfma_f32_16x16x32_bf16 v[24:27], v[84:87], v[192:195], v[24:27]
	v_mfma_f32_16x16x32_bf16 v[12:15], v[68:71], v[200:203], v[12:15]
	v_mfma_f32_16x16x32_bf16 v[8:11], v[84:87], v[200:203], v[8:11]
	s_setprio 0
	s_barrier
	s_add_u32 s30, s30, 0x20080
	s_addc_u32 s31, s31, 0
	s_add_i32 s34, s34, s42
	v_lshl_add_u64 v[64:65], s[30:31], 0, v[148:149]
	s_mov_b32 m0, s34
	s_nop 0
	global_load_lds_dwordx4 v[64:65], off
	v_lshl_add_u64 v[64:65], s[30:31], 0, v[144:145]
	s_add_i32 m0, s34, 0x2000
	s_nop 0
	global_load_lds_dwordx4 v[64:65], off
	s_waitcnt vmcnt(6)
	s_barrier
	s_setprio 1
	v_mfma_f32_16x16x32_bf16 v[52:55], v[204:207], v[162:165], v[52:55]
	v_mfma_f32_16x16x32_bf16 v[48:51], v[212:215], v[162:165], v[48:51]
	v_mfma_f32_16x16x32_bf16 v[36:39], v[204:207], v[180:183], v[36:39]
	v_mfma_f32_16x16x32_bf16 v[32:35], v[212:215], v[180:183], v[32:35]
	v_mfma_f32_16x16x32_bf16 v[20:23], v[204:207], v[188:191], v[20:23]
	v_mfma_f32_16x16x32_bf16 v[16:19], v[212:215], v[188:191], v[16:19]
	v_mfma_f32_16x16x32_bf16 v[4:7], v[204:207], v[196:199], v[4:7]
	v_mfma_f32_16x16x32_bf16 v[0:3], v[212:215], v[196:199], v[0:3]
	v_mfma_f32_16x16x32_bf16 v[52:55], v[208:211], v[166:169], v[52:55]
	v_mfma_f32_16x16x32_bf16 v[48:51], v[216:219], v[166:169], v[48:51]
	v_mfma_f32_16x16x32_bf16 v[36:39], v[208:211], v[184:187], v[36:39]
	v_mfma_f32_16x16x32_bf16 v[32:35], v[216:219], v[184:187], v[32:35]
	v_mfma_f32_16x16x32_bf16 v[20:23], v[208:211], v[192:195], v[20:23]
	v_mfma_f32_16x16x32_bf16 v[16:19], v[216:219], v[192:195], v[16:19]
	v_mfma_f32_16x16x32_bf16 v[4:7], v[208:211], v[200:203], v[4:7]
	v_mfma_f32_16x16x32_bf16 v[0:3], v[216:219], v[200:203], v[0:3]
	s_setprio 0
	s_add_i32 s65, s65, 2
	s_add_u32 s0, s0, 0x100
	s_addc_u32 s1, s1, 0
	s_add_u32 s63, s63, 0x100
	s_addc_u32 s64, s64, 0
	s_cmp_gt_u32 s65, 1
	s_barrier
	s_cbranch_scc0 .LBB0_541
	s_lshl_b32 s0, s33, 8
	s_and_b32 s0, s0, 0x300
	v_readlane_b32 s64, v234, 11
	v_lshl_add_u32 v164, s60, 8, v172
	v_or_b32_e32 v179, s0, v174
	s_cmp_gt_u32 s33, 3
	s_mov_b64 s[0:1], -1
	v_readlane_b32 s65, v234, 12
	v_readlane_b32 s66, v234, 13
	v_readlane_b32 s67, v234, 14
	s_cbranch_scc0 .LBB0_548
	s_cmp_gt_u32 s33, 7
	s_cbranch_scc0 .LBB0_545
	v_lshlrev_b32_e32 v152, 1, v179
	v_ashrrev_i32_e32 v165, 31, v164
	v_lshl_add_u64 v[70:71], s[10:11], 0, v[152:153]
	v_lshlrev_b64 v[64:65], 11, v[164:165]
	v_pk_add_f32 v[68:69], v[142:143], 0 op_sel_hi:[1,0]
	v_pk_add_f32 v[66:67], v[140:141], 0 op_sel_hi:[1,0]
	v_pk_add_f32 v[80:81], v[138:139], 0 op_sel_hi:[1,0]
	v_pk_add_f32 v[82:83], v[136:137], 0 op_sel_hi:[1,0]
	v_lshl_add_u64 v[64:65], v[70:71], 0, v[64:65]
	v_cvt_pk_bf16_f32 v66, v66, v67
	v_cvt_pk_bf16_f32 v67, v68, v69
	v_cvt_pk_bf16_f32 v68, v82, v83
	v_cvt_pk_bf16_f32 v69, v80, v81
	global_store_dwordx4 v[64:65], v[66:69], off
	v_pk_add_f32 v[80:81], v[130:131], 0 op_sel_hi:[1,0]
	v_pk_add_f32 v[82:83], v[128:129], 0 op_sel_hi:[1,0]
	v_pk_add_f32 v[68:69], v[134:135], 0 op_sel_hi:[1,0]
	v_pk_add_f32 v[66:67], v[132:133], 0 op_sel_hi:[1,0]
	v_pk_add_f32 v[84:85], v[120:121], 0 op_sel_hi:[1,0]
	v_cvt_pk_bf16_f32 v66, v66, v67
	v_cvt_pk_bf16_f32 v67, v68, v69
	v_cvt_pk_bf16_f32 v68, v82, v83
	v_cvt_pk_bf16_f32 v69, v80, v81
	global_store_dwordx4 v[64:65], v[66:69], off offset:256
	v_pk_add_f32 v[82:83], v[122:123], 0 op_sel_hi:[1,0]
	v_lshl_add_u64 v[166:167], v[64:65], 0, s[20:21]
	v_or_b32_e32 v66, 16, v164
	v_ashrrev_i32_e32 v67, 31, v66
	v_lshlrev_b64 v[66:67], 11, v[66:67]
	v_lshl_add_u64 v[80:81], v[70:71], 0, v[66:67]
	v_pk_add_f32 v[68:69], v[126:127], 0 op_sel_hi:[1,0]
	v_pk_add_f32 v[66:67], v[124:125], 0 op_sel_hi:[1,0]
	s_mov_b64 s[0:1], 0
	v_cvt_pk_bf16_f32 v66, v66, v67
	v_cvt_pk_bf16_f32 v67, v68, v69
	v_cvt_pk_bf16_f32 v68, v84, v85
	v_cvt_pk_bf16_f32 v69, v82, v83
	global_store_dwordx4 v[80:81], v[66:69], off
	v_pk_add_f32 v[82:83], v[114:115], 0 op_sel_hi:[1,0]
	v_pk_add_f32 v[84:85], v[112:113], 0 op_sel_hi:[1,0]
	v_pk_add_f32 v[68:69], v[118:119], 0 op_sel_hi:[1,0]
	v_pk_add_f32 v[66:67], v[116:117], 0 op_sel_hi:[1,0]
	s_nop 0
	v_cvt_pk_bf16_f32 v66, v66, v67
	v_cvt_pk_bf16_f32 v67, v68, v69
	v_cvt_pk_bf16_f32 v68, v84, v85
	v_cvt_pk_bf16_f32 v69, v82, v83
	global_store_dwordx4 v[80:81], v[66:69], off offset:256
	v_pk_add_f32 v[82:83], v[106:107], 0 op_sel_hi:[1,0]
	v_pk_add_f32 v[84:85], v[104:105], 0 op_sel_hi:[1,0]
	v_or_b32_e32 v66, 32, v164
	v_ashrrev_i32_e32 v67, 31, v66
	v_lshlrev_b64 v[66:67], 11, v[66:67]
	v_lshl_add_u64 v[80:81], v[70:71], 0, v[66:67]
	v_pk_add_f32 v[68:69], v[110:111], 0 op_sel_hi:[1,0]
	v_pk_add_f32 v[66:67], v[108:109], 0 op_sel_hi:[1,0]
	s_nop 0
	v_cvt_pk_bf16_f32 v66, v66, v67
	v_cvt_pk_bf16_f32 v67, v68, v69
	v_cvt_pk_bf16_f32 v68, v84, v85
	v_cvt_pk_bf16_f32 v69, v82, v83
	global_store_dwordx4 v[80:81], v[66:69], off
	v_pk_add_f32 v[82:83], v[98:99], 0 op_sel_hi:[1,0]
	v_pk_add_f32 v[84:85], v[96:97], 0 op_sel_hi:[1,0]
	v_pk_add_f32 v[68:69], v[102:103], 0 op_sel_hi:[1,0]
	v_pk_add_f32 v[66:67], v[100:101], 0 op_sel_hi:[1,0]
	s_nop 0
	v_cvt_pk_bf16_f32 v66, v66, v67
	v_cvt_pk_bf16_f32 v67, v68, v69
	v_cvt_pk_bf16_f32 v68, v84, v85
	v_cvt_pk_bf16_f32 v69, v82, v83
	global_store_dwordx4 v[80:81], v[66:69], off offset:256
	v_pk_add_f32 v[80:81], v[90:91], 0 op_sel_hi:[1,0]
	v_pk_add_f32 v[82:83], v[88:89], 0 op_sel_hi:[1,0]
	v_or_b32_e32 v66, 48, v164
	v_ashrrev_i32_e32 v67, 31, v66
	v_lshlrev_b64 v[66:67], 11, v[66:67]
	v_lshl_add_u64 v[70:71], v[70:71], 0, v[66:67]
	v_pk_add_f32 v[68:69], v[94:95], 0 op_sel_hi:[1,0]
	v_pk_add_f32 v[66:67], v[92:93], 0 op_sel_hi:[1,0]
	s_nop 0
	v_cvt_pk_bf16_f32 v66, v66, v67
	v_cvt_pk_bf16_f32 v67, v68, v69
	v_cvt_pk_bf16_f32 v68, v82, v83
	v_cvt_pk_bf16_f32 v69, v80, v81
	global_store_dwordx4 v[70:71], v[66:69], off
	v_pk_add_f32 v[80:81], v[74:75], 0 op_sel_hi:[1,0]
	v_pk_add_f32 v[82:83], v[72:73], 0 op_sel_hi:[1,0]
	v_pk_add_f32 v[68:69], v[78:79], 0 op_sel_hi:[1,0]
	v_pk_add_f32 v[66:67], v[76:77], 0 op_sel_hi:[1,0]
	s_nop 0
	v_cvt_pk_bf16_f32 v66, v66, v67
	v_cvt_pk_bf16_f32 v67, v68, v69
	v_cvt_pk_bf16_f32 v68, v82, v83
	v_cvt_pk_bf16_f32 v69, v80, v81
	global_store_dwordx4 v[70:71], v[66:69], off offset:256
	v_pk_add_f32 v[80:81], v[58:59], 0 op_sel_hi:[1,0]
	v_pk_add_f32 v[82:83], v[56:57], 0 op_sel_hi:[1,0]
	v_pk_add_f32 v[68:69], v[62:63], 0 op_sel_hi:[1,0]
	v_pk_add_f32 v[66:67], v[60:61], 0 op_sel_hi:[1,0]
	v_lshl_add_u64 v[70:71], v[64:65], 0, s[14:15]
	v_cvt_pk_bf16_f32 v66, v66, v67
	v_cvt_pk_bf16_f32 v67, v68, v69
	v_cvt_pk_bf16_f32 v69, v80, v81
	v_add_co_u32_e32 v80, vcc, s52, v64
	v_cvt_pk_bf16_f32 v68, v82, v83
	s_nop 0
	v_addc_co_u32_e32 v81, vcc, 0, v65, vcc
	global_store_dwordx4 v[80:81], v[66:69], off
	v_pk_add_f32 v[80:81], v[50:51], 0 op_sel_hi:[1,0]
	v_pk_add_f32 v[82:83], v[48:49], 0 op_sel_hi:[1,0]
	v_pk_add_f32 v[68:69], v[54:55], 0 op_sel_hi:[1,0]
	v_pk_add_f32 v[66:67], v[52:53], 0 op_sel_hi:[1,0]
	s_nop 0
	v_cvt_pk_bf16_f32 v66, v66, v67
	v_cvt_pk_bf16_f32 v67, v68, v69
	v_cvt_pk_bf16_f32 v68, v82, v83
	v_cvt_pk_bf16_f32 v69, v80, v81
	global_store_dwordx4 v[70:71], v[66:69], off offset:256
	v_pk_add_f32 v[80:81], v[42:43], 0 op_sel_hi:[1,0]
	v_pk_add_f32 v[82:83], v[40:41], 0 op_sel_hi:[1,0]
	v_pk_add_f32 v[68:69], v[46:47], 0 op_sel_hi:[1,0]
	v_pk_add_f32 v[66:67], v[44:45], 0 op_sel_hi:[1,0]
	v_lshl_add_u64 v[70:71], v[64:65], 0, s[16:17]
	v_cvt_pk_bf16_f32 v66, v66, v67
	v_cvt_pk_bf16_f32 v67, v68, v69
	v_cvt_pk_bf16_f32 v69, v80, v81
	v_add_co_u32_e32 v80, vcc, s53, v64
	v_cvt_pk_bf16_f32 v68, v82, v83
	s_nop 0
	v_addc_co_u32_e32 v81, vcc, 0, v65, vcc
	global_store_dwordx4 v[80:81], v[66:69], off
	v_pk_add_f32 v[80:81], v[34:35], 0 op_sel_hi:[1,0]
	v_pk_add_f32 v[82:83], v[32:33], 0 op_sel_hi:[1,0]
	v_pk_add_f32 v[68:69], v[38:39], 0 op_sel_hi:[1,0]
	v_pk_add_f32 v[66:67], v[36:37], 0 op_sel_hi:[1,0]
	s_nop 0
	v_cvt_pk_bf16_f32 v66, v66, v67
	v_cvt_pk_bf16_f32 v67, v68, v69
	v_cvt_pk_bf16_f32 v68, v82, v83
	v_cvt_pk_bf16_f32 v69, v80, v81
	global_store_dwordx4 v[70:71], v[66:69], off offset:256
	v_pk_add_f32 v[80:81], v[26:27], 0 op_sel_hi:[1,0]
	v_pk_add_f32 v[82:83], v[24:25], 0 op_sel_hi:[1,0]
	v_pk_add_f32 v[68:69], v[30:31], 0 op_sel_hi:[1,0]
	v_pk_add_f32 v[66:67], v[28:29], 0 op_sel_hi:[1,0]
	v_lshl_add_u64 v[70:71], v[64:65], 0, s[18:19]
	v_cvt_pk_bf16_f32 v66, v66, v67
	v_cvt_pk_bf16_f32 v67, v68, v69
	v_cvt_pk_bf16_f32 v69, v80, v81
	v_add_co_u32_e32 v80, vcc, s54, v64
	v_cvt_pk_bf16_f32 v68, v82, v83
	s_nop 0
	v_addc_co_u32_e32 v81, vcc, 0, v65, vcc
	global_store_dwordx4 v[80:81], v[66:69], off
	v_pk_add_f32 v[80:81], v[18:19], 0 op_sel_hi:[1,0]
	v_pk_add_f32 v[82:83], v[16:17], 0 op_sel_hi:[1,0]
	v_pk_add_f32 v[68:69], v[22:23], 0 op_sel_hi:[1,0]
	v_pk_add_f32 v[66:67], v[20:21], 0 op_sel_hi:[1,0]
	v_add_co_u32_e32 v64, vcc, s55, v64
	v_cvt_pk_bf16_f32 v66, v66, v67
	v_cvt_pk_bf16_f32 v67, v68, v69
	v_cvt_pk_bf16_f32 v68, v82, v83
	v_cvt_pk_bf16_f32 v69, v80, v81
	global_store_dwordx4 v[70:71], v[66:69], off offset:256
	v_pk_add_f32 v[70:71], v[10:11], 0 op_sel_hi:[1,0]
	v_pk_add_f32 v[80:81], v[8:9], 0 op_sel_hi:[1,0]
	v_pk_add_f32 v[68:69], v[14:15], 0 op_sel_hi:[1,0]
	v_pk_add_f32 v[66:67], v[12:13], 0 op_sel_hi:[1,0]
	v_addc_co_u32_e32 v65, vcc, 0, v65, vcc
	v_cvt_pk_bf16_f32 v66, v66, v67
	v_cvt_pk_bf16_f32 v67, v68, v69
	v_cvt_pk_bf16_f32 v68, v80, v81
	v_cvt_pk_bf16_f32 v69, v70, v71
	global_store_dwordx4 v[64:65], v[66:69], off
	v_pk_add_f32 v[64:65], v[4:5], 0 op_sel_hi:[1,0]
	v_pk_add_f32 v[70:71], v[0:1], 0 op_sel_hi:[1,0]
	v_pk_add_f32 v[66:67], v[6:7], 0 op_sel_hi:[1,0]
	v_pk_add_f32 v[68:69], v[2:3], 0 op_sel_hi:[1,0]
	v_cvt_pk_bf16_f32 v64, v64, v65
	v_cvt_pk_bf16_f32 v65, v66, v67
	v_cvt_pk_bf16_f32 v66, v70, v71
